# grid barrier: blocks released by their XCD leader invalidate their CU L1 only after phases 3 and 7 (every re-used buffer region is separated by one of those); leader path unchanged
# speedup vs baseline: 1.0369x; 1.0314x over previous
; DEVINL unsigned xb_ld(unsigned* p) { return __hip_atomic_load(p, __ATOMIC_RELAXED, __HIP_MEMORY_SCOPE_AGENT); }
; #define XB_SPIN(cond, bar) do { unsigned _sp = 0; while (cond) { __builtin_amdgcn_s_sleep(1); \
;     if ((++_sp & 255u) == 0u) { if (xb_ld(&(bar)[XB_TMO])) break; if (_sp > XB_SPIN_CAP) { atomicAdd(&(bar)[XB_TMO], 1u); break; } } } } while (0)
; DEVINL void xcd_barrier(XcdBarrier& b) {
;     ...
;     } else {
;       XB_SPIN(xb_ld(&bar[XB_XGEN(b.x)]) == gen, bar);
;       __builtin_amdgcn_fence(__ATOMIC_ACQUIRE, "agent");
;       asm volatile("s_waitcnt vmcnt(0)" ::: "memory");
;     }
.LBB0_1580:
	s_or_b64 exec, exec, s[38:39]
	s_waitcnt vmcnt(0)
	s_cmp_eq_u32 s29, 3
	s_cbranch_scc1 .LBAR_l1inv
	s_cmp_eq_u32 s29, 7
	s_cbranch_scc1 .LBAR_l1inv
	s_branch .LBAR_l1done
.LBAR_l1inv:
	buffer_inv sc1
.LBAR_l1done:
	s_waitcnt vmcnt(0)
.LBB0_1581:
	s_andn2_saveexec_b64 s[36:37], s[36:37]
	s_cbranch_execnz .LBB0_1582
	s_getpc_b64 s[98:99]
